# out-proj (256-row tiles) epilogue rewritten: gate row loaded once, x rows prefetched 8 deep with counted vmcnt instead of a vmcnt(0) drain per 16-byte store
# speedup vs baseline: 1.0492x; 1.0175x over previous
; #define RAW_BARRIER() do { asm volatile("s_waitcnt lgkmcnt(0)" ::: "memory"); __builtin_amdgcn_s_barrier(); } while (0)
;   DI void operator()(int mt, int nt, int wm, int wn, int r, int h, f32x16 (&acc)[WM][2]) const {
;     constexpr int LD = 132;
;     float* T = (float*)smem;
;     const int tid = wm * 128 + wn * 64 + h * 32 + r;
; #pragma unroll
;     for (int ps = 0; ps < WM / 2; ++ps) {
;       RAW_BARRIER();
; #pragma unroll
;       for (int mh = 0; mh < 2; ++mh)
; #pragma unroll
;         for (int ni = 0; ni < 2; ++ni)
; #pragma unroll
;           for (int i = 0; i < 16; ++i)
;             T[(wm * 64 + mh * 32 + (i & 3) + 8 * (i >> 2) + 4 * h) * LD + wn * 64 + ni * 32 + r] = acc[ps * 2 + mh][ni][i];
;       RAW_BARRIER();
; #pragma unroll 4
;       for (int j = 0; j < 16; ++j) {
;         const int id = tid + 256 * j;
;         const int lr = id >> 5, cc = id & 31;
;         const int row = mt * (WM * 64) + (lr >> 6) * (WM * 32) + ps * 64 + (lr & 63);
;         const int b = row / NTOK, t = row % NTOK;
;         const bool isctx = t < NCTX;
;         if (isctx && l == 1) continue;
;         const int col = nt * 128 + cc * 4;
;         const float4 a = *(const float4*)(T + lr * LD + cc * 4);
;         const float4 g = *(const float4*)(MOD + ((size_t)l * 9 + (isctx ? 8 : b)) * 3072 + 2048 + col);
;         const float4 xo = *(const float4*)(xsrc_row(*p, l, b, t) + col);
;         float* dst = (isctx ? (float*)(p->ws + WS_XRC) + ((size_t)b * NCTX + t) * DM : p->out + ((size_t)b * NLAT + (t - NCTX)) * DM) + col;
;         *(float4*)dst = make_float4(xo.x + g.x * a.x, xo.y + g.y * a.y, xo.z + g.z * a.z, xo.w + g.w * a.w);
.LBB0_1062:
	s_waitcnt lgkmcnt(0)
	s_setprio 1
	v_mfma_f32_32x32x16_bf16 v[96:111], v[148:151], v[132:135], v[96:111]
	v_mfma_f32_32x32x16_bf16 v[80:95], v[140:143], v[144:147], v[80:95]
	v_mfma_f32_32x32x16_bf16 v[64:79], v[140:143], v[132:135], v[64:79]
	v_mfma_f32_32x32x16_bf16 v[48:63], v[136:139], v[144:147], v[48:63]
	v_mfma_f32_32x32x16_bf16 v[16:31], v[128:131], v[144:147], v[16:31]
	v_mfma_f32_32x32x16_bf16 v[112:127], v[148:151], v[144:147], v[112:127]
	s_setprio 0
	v_mov_b32_e32 v140, v156
	v_mov_b32_e32 v144, v155
	s_waitcnt lgkmcnt(0)
	s_barrier
	v_lshl_add_u32 v141, v140, 2, v166
	v_add_u32_e32 v146, v144, v165
	v_mul_lo_u32 v141, v141, s66
	v_lshl_add_u32 v141, v146, 2, v141
	s_waitcnt vmcnt(0)
	s_nop 2
	ds_write2_b32 v141, v112, v96 offset1:32
	ds_write2_b32 v141, v113, v97 offset0:132 offset1:164
	v_add_u32_e32 v96, 0x400, v141
	ds_write2_b32 v96, v114, v98 offset0:8 offset1:40
	ds_write2_b32 v96, v115, v99 offset0:140 offset1:172
	v_add_u32_e32 v97, 0x1000, v141
	v_add_u32_e32 v98, 0x1400, v141
	v_add_u32_e32 v99, 0x2000, v141
	ds_write2_b32 v97, v116, v100 offset0:32 offset1:64
	ds_write2_b32 v97, v117, v101 offset0:164 offset1:196
	ds_write2_b32 v98, v118, v102 offset0:40 offset1:72
	ds_write2_b32 v98, v119, v103 offset0:172 offset1:204
	ds_write2_b32 v99, v120, v104 offset0:64 offset1:96
	ds_write2_b32 v99, v121, v105 offset0:196 offset1:228
	v_add_u32_e32 v100, 0x2400, v141
	v_add_u32_e32 v105, 0x4000, v141
	ds_write2_b32 v100, v122, v106 offset0:72 offset1:104
	ds_write2_b32 v100, v123, v107 offset0:204 offset1:236
	v_add_u32_e32 v101, 0x3000, v141
	v_add_u32_e32 v102, 0x3200, v141
	v_add_u32_e32 v103, 0x3400, v141
	v_add_u32_e32 v104, 0x3600, v141
	ds_write2_b32 v105, v80, v64 offset0:128 offset1:160
	v_add_u32_e32 v80, 0x4400, v141
	ds_write2_b32 v101, v124, v108 offset0:96 offset1:128
	ds_write2_b32 v102, v125, v109 offset0:100 offset1:132
	ds_write2_b32 v103, v126, v110 offset0:104 offset1:136
	ds_write2_b32 v104, v127, v111 offset0:108 offset1:140
	ds_write2_b32 v80, v81, v65 offset0:4 offset1:36
	ds_write2_b32 v80, v82, v66 offset0:136 offset1:168
	v_add_u32_e32 v81, 0x4800, v141
	ds_write2_b32 v81, v83, v67 offset0:12 offset1:44
	v_add_u32_e32 v82, 0x5000, v141
	v_add_u32_e32 v83, 0x5400, v141
	ds_write2_b32 v82, v84, v68 offset0:160 offset1:192
	ds_write2_b32 v83, v85, v69 offset0:36 offset1:68
	ds_write2_b32 v83, v86, v70 offset0:168 offset1:200
	v_add_u32_e32 v69, 0x5800, v141
	ds_write2_b32 v69, v87, v71 offset0:44 offset1:76
	v_add_u32_e32 v70, 0x6000, v141
	v_add_u32_e32 v71, 0x6400, v141
	ds_write2_b32 v70, v88, v72 offset0:192 offset1:224
	ds_write2_b32 v71, v89, v73 offset0:68 offset1:100
	ds_write2_b32 v71, v90, v74 offset0:200 offset1:232
	v_add_u32_e32 v72, 0x6800, v141
	v_add_u32_e32 v73, 0x7200, v141
	v_lshlrev_b32_e32 v145, 5, v140
	v_lshlrev_b32_e32 v140, 2, v144
	ds_write2_b32 v72, v91, v75 offset0:76 offset1:108
	ds_write2_b32 v73, v92, v76 offset0:96 offset1:128
	v_add_u32_e32 v74, 0x7400, v141
	v_add_u32_e32 v75, 0x7600, v141
	v_add_u32_e32 v76, 0x7800, v141
	v_and_b32_e32 v140, 0x7c, v140
	ds_write2_b32 v74, v93, v77 offset0:100 offset1:132
	ds_write2_b32 v75, v94, v78 offset0:104 offset1:136
	ds_write2_b32 v76, v95, v79 offset0:108 offset1:140
	v_or_b32_e32 v142, s26, v140
	s_waitcnt lgkmcnt(0)
	v_ashrrev_i32_e32 v143, 31, v142
	v_lshlrev_b32_e32 v140, 2, v140
	v_add3_u32 v68, v167, v144, v145
	s_mov_b32 s6, 0
	v_lshlrev_b64 v[64:65], 2, v[142:143]
	s_barrier
	v_ashrrev_i32_e32 v66, 5, v68
	v_add_u32_e32 v78, s25, v66
	v_mul_hi_i32 v77, v78, s55
	v_lshrrev_b32_e32 v79, 31, v77
	v_ashrrev_i32_e32 v77, 9, v77
	v_add_u32_e32 v77, v77, v79
	v_mul_i32_i24_e32 v79, 0x900, v77
	v_sub_u32_e32 v78, v78, v79
	v_mad_u32_u24 v67, v66, s66, v140
	v_add_u32_e32 v66, s13, v77
	v_mul_hi_i32_i24_e32 v85, 0x3000, v66
	v_mul_i32_i24_e32 v84, 0x3000, v66
	v_lshl_add_u64 v[84:85], s[0:1], 0, v[84:85]
	v_lshl_add_u64 v[84:85], v[84:85], 0, v[64:65]
	s_mov_b64 s[8:9], 0x2000
	v_lshl_add_u64 v[84:85], v[84:85], 0, s[8:9]
	global_load_dwordx4 v[88:91], v[84:85], off
	v_add_u32_e32 v78, 0xffffff00, v78
	v_mov_b32_e32 v79, 0
	v_lshlrev_b64 v[78:79], 12, v[78:79]
	v_mov_b32_e32 v86, v77
	v_mov_b32_e32 v87, 0
	v_lshlrev_b64 v[86:87], 23, v[86:87]
	v_lshl_add_u64 v[86:87], v[86:87], 0, v[78:79]
	v_lshl_add_u64 v[86:87], v[86:87], 0, v[64:65]
	v_mov_b32_e32 v92, s21
	v_mov_b32_e32 v93, s20
	v_lshl_add_u64 v[92:93], v[92:93], 0, v[86:87]
	v_lshl_add_u64 v[94:95], s[36:37], 0, v[86:87]
	global_load_dwordx4 v[218:221], v[92:93], off
	s_mov_b64 s[8:9], 0x8000
	v_lshl_add_u64 v[84:85], v[92:93], 0, s[8:9]
	global_load_dwordx4 v[222:225], v[84:85], off
	s_mov_b64 s[8:9], 0x10000
	v_lshl_add_u64 v[84:85], v[92:93], 0, s[8:9]
	global_load_dwordx4 v[226:229], v[84:85], off
	s_mov_b64 s[8:9], 0x18000
	v_lshl_add_u64 v[84:85], v[92:93], 0, s[8:9]
	global_load_dwordx4 v[230:233], v[84:85], off
	s_mov_b64 s[8:9], 0x20000
	v_lshl_add_u64 v[84:85], v[92:93], 0, s[8:9]
	global_load_dwordx4 v[234:237], v[84:85], off
	s_mov_b64 s[8:9], 0x28000
	v_lshl_add_u64 v[84:85], v[92:93], 0, s[8:9]
	global_load_dwordx4 v[238:241], v[84:85], off
	s_mov_b64 s[8:9], 0x30000
	v_lshl_add_u64 v[84:85], v[92:93], 0, s[8:9]
	global_load_dwordx4 v[242:245], v[84:85], off
	s_mov_b64 s[8:9], 0x38000
	v_lshl_add_u64 v[84:85], v[92:93], 0, s[8:9]
	global_load_dwordx4 v[246:249], v[84:85], off
	ds_read_b128 v[108:111], v67
	ds_read_b128 v[112:115], v67 offset:4224
	ds_read_b128 v[116:119], v67 offset:8448
	ds_read_b128 v[120:123], v67 offset:12672
	s_waitcnt vmcnt(7) lgkmcnt(3)
;   DI void operator()(int mt, int nt, int wm, int wn, int r, int h, f32x16 (&acc)[WM][2]) const {
;     ...
; #pragma unroll 4
;       for (int j = 0; j < 16; ++j) {
;         const int id = tid + 256 * j;
;         const int lr = id >> 5, cc = id & 31;
;         const int row = mt * (WM * 64) + (lr >> 6) * (WM * 32) + ps * 64 + (lr & 63);
;         const int b = row / NTOK, t = row % NTOK;
;         const bool isctx = t < NCTX;
;         if (isctx && l == 1) continue;
;         const int col = nt * 128 + cc * 4;
;         const float4 a = *(const float4*)(T + lr * LD + cc * 4);
;         const float4 g = *(const float4*)(MOD + ((size_t)l * 9 + (isctx ? 8 : b)) * 3072 + 2048 + col);
;         const float4 xo = *(const float4*)(xsrc_row(*p, l, b, t) + col);
;         float* dst = (isctx ? (float*)(p->ws + WS_XRC) + ((size_t)b * NCTX + t) * DM : p->out + ((size_t)b * NLAT + (t - NCTX)) * DM) + col;
;         *(float4*)dst = make_float4(xo.x + g.x * a.x, xo.y + g.y * a.y, xo.z + g.z * a.z, xo.w + g.w * a.w);
	v_pk_fma_f32 v[108:109], v[108:109], v[88:89], v[218:219]
	v_pk_fma_f32 v[110:111], v[110:111], v[90:91], v[220:221]
	global_store_dwordx4 v[94:95], v[108:111], off
	s_mov_b64 s[8:9], 0x80000
	v_lshl_add_u64 v[86:87], v[92:93], 0, s[8:9]
	global_load_dwordx4 v[218:221], v[86:87], off
	ds_read_b128 v[108:111], v67 offset:16896
	s_waitcnt vmcnt(8) lgkmcnt(3)
	v_pk_fma_f32 v[112:113], v[112:113], v[88:89], v[222:223]
	v_pk_fma_f32 v[114:115], v[114:115], v[90:91], v[224:225]
	s_mov_b64 s[8:9], 0x8000
	v_lshl_add_u64 v[84:85], v[94:95], 0, s[8:9]
	global_store_dwordx4 v[84:85], v[112:115], off
	s_mov_b64 s[8:9], 0x88000
	v_lshl_add_u64 v[86:87], v[92:93], 0, s[8:9]
	global_load_dwordx4 v[222:225], v[86:87], off
	ds_read_b128 v[112:115], v67 offset:21120
	s_waitcnt vmcnt(9) lgkmcnt(3)
	v_pk_fma_f32 v[116:117], v[116:117], v[88:89], v[226:227]
	v_pk_fma_f32 v[118:119], v[118:119], v[90:91], v[228:229]
	s_mov_b64 s[8:9], 0x10000
	v_lshl_add_u64 v[84:85], v[94:95], 0, s[8:9]
	global_store_dwordx4 v[84:85], v[116:119], off
	s_mov_b64 s[8:9], 0x90000
	v_lshl_add_u64 v[86:87], v[92:93], 0, s[8:9]
	global_load_dwordx4 v[226:229], v[86:87], off
	ds_read_b128 v[116:119], v67 offset:25344
	s_waitcnt vmcnt(10) lgkmcnt(3)
	v_pk_fma_f32 v[120:121], v[120:121], v[88:89], v[230:231]
	v_pk_fma_f32 v[122:123], v[122:123], v[90:91], v[232:233]
	s_mov_b64 s[8:9], 0x18000
	v_lshl_add_u64 v[84:85], v[94:95], 0, s[8:9]
	global_store_dwordx4 v[84:85], v[120:123], off
	s_mov_b64 s[8:9], 0x98000
	v_lshl_add_u64 v[86:87], v[92:93], 0, s[8:9]
	global_load_dwordx4 v[230:233], v[86:87], off
	ds_read_b128 v[120:123], v67 offset:29568
	s_waitcnt vmcnt(11) lgkmcnt(3)
	v_pk_fma_f32 v[108:109], v[108:109], v[88:89], v[234:235]
	v_pk_fma_f32 v[110:111], v[110:111], v[90:91], v[236:237]
	s_mov_b64 s[8:9], 0x20000
	v_lshl_add_u64 v[84:85], v[94:95], 0, s[8:9]
	global_store_dwordx4 v[84:85], v[108:111], off
	s_mov_b64 s[8:9], 0xa0000
	v_lshl_add_u64 v[86:87], v[92:93], 0, s[8:9]
	global_load_dwordx4 v[234:237], v[86:87], off
	ds_read_b128 v[108:111], v67 offset:33792
	s_waitcnt vmcnt(12) lgkmcnt(3)
	v_pk_fma_f32 v[112:113], v[112:113], v[88:89], v[238:239]
	v_pk_fma_f32 v[114:115], v[114:115], v[90:91], v[240:241]
	s_mov_b64 s[8:9], 0x28000
	v_lshl_add_u64 v[84:85], v[94:95], 0, s[8:9]
	global_store_dwordx4 v[84:85], v[112:115], off
	s_mov_b64 s[8:9], 0xa8000
	v_lshl_add_u64 v[86:87], v[92:93], 0, s[8:9]
	global_load_dwordx4 v[238:241], v[86:87], off
	ds_read_b128 v[112:115], v67 offset:38016
	s_waitcnt vmcnt(13) lgkmcnt(3)
	v_pk_fma_f32 v[116:117], v[116:117], v[88:89], v[242:243]
	v_pk_fma_f32 v[118:119], v[118:119], v[90:91], v[244:245]
	s_mov_b64 s[8:9], 0x30000
	v_lshl_add_u64 v[84:85], v[94:95], 0, s[8:9]
	global_store_dwordx4 v[84:85], v[116:119], off
	s_mov_b64 s[8:9], 0xb0000
	v_lshl_add_u64 v[86:87], v[92:93], 0, s[8:9]
	global_load_dwordx4 v[242:245], v[86:87], off
	ds_read_b128 v[116:119], v67 offset:42240
	s_waitcnt vmcnt(14) lgkmcnt(3)
	v_pk_fma_f32 v[120:121], v[120:121], v[88:89], v[246:247]
	v_pk_fma_f32 v[122:123], v[122:123], v[90:91], v[248:249]
	s_mov_b64 s[8:9], 0x38000
	v_lshl_add_u64 v[84:85], v[94:95], 0, s[8:9]
	global_store_dwordx4 v[84:85], v[120:123], off
	s_mov_b64 s[8:9], 0xb8000
	v_lshl_add_u64 v[86:87], v[92:93], 0, s[8:9]
	global_load_dwordx4 v[246:249], v[86:87], off
	ds_read_b128 v[120:123], v67 offset:46464
	s_waitcnt vmcnt(14) lgkmcnt(3)
	v_pk_fma_f32 v[108:109], v[108:109], v[88:89], v[218:219]
	v_pk_fma_f32 v[110:111], v[110:111], v[90:91], v[220:221]
	s_mov_b64 s[8:9], 0x80000
	v_lshl_add_u64 v[84:85], v[94:95], 0, s[8:9]
	global_store_dwordx4 v[84:85], v[108:111], off
	s_nop 1
	ds_read_b128 v[108:111], v67 offset:50688
	s_waitcnt vmcnt(13) lgkmcnt(3)
	v_pk_fma_f32 v[112:113], v[112:113], v[88:89], v[222:223]
	v_pk_fma_f32 v[114:115], v[114:115], v[90:91], v[224:225]
	s_mov_b64 s[8:9], 0x88000
	v_lshl_add_u64 v[84:85], v[94:95], 0, s[8:9]
	global_store_dwordx4 v[84:85], v[112:115], off
	s_nop 1
	ds_read_b128 v[112:115], v67 offset:54912
	s_waitcnt vmcnt(12) lgkmcnt(3)
	v_pk_fma_f32 v[116:117], v[116:117], v[88:89], v[226:227]
	v_pk_fma_f32 v[118:119], v[118:119], v[90:91], v[228:229]
	s_mov_b64 s[8:9], 0x90000
	v_lshl_add_u64 v[84:85], v[94:95], 0, s[8:9]
	global_store_dwordx4 v[84:85], v[116:119], off
	s_nop 1
	ds_read_b128 v[116:119], v67 offset:59136
	s_waitcnt vmcnt(11) lgkmcnt(3)
	v_pk_fma_f32 v[120:121], v[120:121], v[88:89], v[230:231]
	v_pk_fma_f32 v[122:123], v[122:123], v[90:91], v[232:233]
	s_mov_b64 s[8:9], 0x98000
	v_lshl_add_u64 v[84:85], v[94:95], 0, s[8:9]
	global_store_dwordx4 v[84:85], v[120:123], off
	s_nop 1
	ds_read_b128 v[120:123], v67 offset:63360
	s_waitcnt vmcnt(10) lgkmcnt(3)
	v_pk_fma_f32 v[108:109], v[108:109], v[88:89], v[234:235]
	v_pk_fma_f32 v[110:111], v[110:111], v[90:91], v[236:237]
	s_mov_b64 s[8:9], 0xa0000
	v_lshl_add_u64 v[84:85], v[94:95], 0, s[8:9]
	global_store_dwordx4 v[84:85], v[108:111], off
	s_waitcnt vmcnt(9) lgkmcnt(2)
	v_pk_fma_f32 v[112:113], v[112:113], v[88:89], v[238:239]
	v_pk_fma_f32 v[114:115], v[114:115], v[90:91], v[240:241]
	s_mov_b64 s[8:9], 0xa8000
	v_lshl_add_u64 v[84:85], v[94:95], 0, s[8:9]
	global_store_dwordx4 v[84:85], v[112:115], off
	s_waitcnt vmcnt(8) lgkmcnt(1)
	v_pk_fma_f32 v[116:117], v[116:117], v[88:89], v[242:243]
	v_pk_fma_f32 v[118:119], v[118:119], v[90:91], v[244:245]
	s_mov_b64 s[8:9], 0xb0000
	v_lshl_add_u64 v[84:85], v[94:95], 0, s[8:9]
	global_store_dwordx4 v[84:85], v[116:119], off
	s_waitcnt vmcnt(7) lgkmcnt(0)
	v_pk_fma_f32 v[120:121], v[120:121], v[88:89], v[246:247]
	v_pk_fma_f32 v[122:123], v[122:123], v[90:91], v[248:249]
	s_mov_b64 s[8:9], 0xb8000
	v_lshl_add_u64 v[84:85], v[94:95], 0, s[8:9]
	global_store_dwordx4 v[84:85], v[120:123], off
; #define RAW_BARRIER() do { asm volatile("s_waitcnt lgkmcnt(0)" ::: "memory"); __builtin_amdgcn_s_barrier(); } while (0)
;   DI void operator()(int mt, int nt, int wm, int wn, int r, int h, f32x16 (&acc)[WM][2]) const {
;     ...
;     for (int ps = 0; ps < WM / 2; ++ps) {
;       RAW_BARRIER();
; #pragma unroll
;       for (int mh = 0; mh < 2; ++mh)
; #pragma unroll
;         for (int ni = 0; ni < 2; ++ni)
; #pragma unroll
;           for (int i = 0; i < 16; ++i)
;             T[(wm * 64 + mh * 32 + (i & 3) + 8 * (i >> 2) + 4 * h) * LD + wn * 64 + ni * 32 + r] = acc[ps * 2 + mh][ni][i];
;       RAW_BARRIER();
; #pragma unroll 4
;       for (int j = 0; j < 16; ++j) {
;         const int id = tid + 256 * j;
;         const int lr = id >> 5, cc = id & 31;
;         const int row = mt * (WM * 64) + (lr >> 6) * (WM * 32) + ps * 64 + (lr & 63);
;         const int b = row / NTOK, t = row % NTOK;
;         const bool isctx = t < NCTX;
;         if (isctx && l == 1) continue;
;         const int col = nt * 128 + cc * 4;
;         const float4 a = *(const float4*)(T + lr * LD + cc * 4);
;         const float4 g = *(const float4*)(MOD + ((size_t)l * 9 + (isctx ? 8 : b)) * 3072 + 2048 + col);
;         const float4 xo = *(const float4*)(xsrc_row(*p, l, b, t) + col);
;         float* dst = (isctx ? (float*)(p->ws + WS_XRC) + ((size_t)b * NCTX + t) * DM : p->out + ((size_t)b * NLAT + (t - NCTX)) * DM) + col;
;         *(float4*)dst = make_float4(xo.x + g.x * a.x, xo.y + g.y * a.y, xo.z + g.z * a.z, xo.w + g.w * a.w);
.LBB0_1072:
	v_mfma_f32_32x32x16_bf16 v[32:47], v[136:139], v[132:135], v[32:47]
	s_waitcnt lgkmcnt(0)
	s_barrier
	s_or_b32 s6, s25, 64
	s_mov_b32 s7, 0
	s_nop 8
	ds_write2_b32 v141, v48, v32 offset1:32
	ds_write2_b32 v141, v49, v33 offset0:132 offset1:164
	ds_write2_b32 v96, v50, v34 offset0:8 offset1:40
	ds_write2_b32 v96, v51, v35 offset0:140 offset1:172
	ds_write2_b32 v97, v52, v36 offset0:32 offset1:64
	ds_write2_b32 v97, v53, v37 offset0:164 offset1:196
	ds_write2_b32 v98, v54, v38 offset0:40 offset1:72
	ds_write2_b32 v98, v55, v39 offset0:172 offset1:204
	ds_write2_b32 v99, v56, v40 offset0:64 offset1:96
	ds_write2_b32 v99, v57, v41 offset0:196 offset1:228
	ds_write2_b32 v100, v58, v42 offset0:72 offset1:104
	v_mfma_f32_32x32x16_bf16 v[0:15], v[128:131], v[132:135], v[0:15]
	ds_write2_b32 v100, v59, v43 offset0:204 offset1:236
	ds_write2_b32 v101, v60, v44 offset0:96 offset1:128
	ds_write2_b32 v102, v61, v45 offset0:100 offset1:132
	ds_write2_b32 v103, v62, v46 offset0:104 offset1:136
	ds_write2_b32 v104, v63, v47 offset0:108 offset1:140
	s_nop 6
	ds_write2_b32 v105, v16, v0 offset0:128 offset1:160
	ds_write2_b32 v80, v17, v1 offset0:4 offset1:36
	ds_write2_b32 v80, v18, v2 offset0:136 offset1:168
	ds_write2_b32 v81, v19, v3 offset0:12 offset1:44
	ds_write2_b32 v82, v20, v4 offset0:160 offset1:192
	ds_write2_b32 v83, v21, v5 offset0:36 offset1:68
	ds_write2_b32 v83, v22, v6 offset0:168 offset1:200
	ds_write2_b32 v69, v23, v7 offset0:44 offset1:76
	ds_write2_b32 v70, v24, v8 offset0:192 offset1:224
	ds_write2_b32 v71, v25, v9 offset0:68 offset1:100
	ds_write2_b32 v71, v26, v10 offset0:200 offset1:232
	ds_write2_b32 v72, v27, v11 offset0:76 offset1:108
	ds_write2_b32 v73, v28, v12 offset0:96 offset1:128
	ds_write2_b32 v74, v29, v13 offset0:100 offset1:132
	ds_write2_b32 v75, v30, v14 offset0:104 offset1:136
	ds_write2_b32 v76, v31, v15 offset0:108 offset1:140
	s_waitcnt lgkmcnt(0)
	s_barrier
	v_ashrrev_i32_e32 v66, 5, v68
	v_add_u32_e32 v78, s6, v66
	v_mul_hi_i32 v77, v78, s55
	v_lshrrev_b32_e32 v79, 31, v77
	v_ashrrev_i32_e32 v77, 9, v77
	v_add_u32_e32 v77, v77, v79
	v_mul_i32_i24_e32 v79, 0x900, v77
	v_sub_u32_e32 v78, v78, v79
	v_mad_u32_u24 v67, v66, s66, v140
	v_add_u32_e32 v66, s13, v77
	v_mul_hi_i32_i24_e32 v85, 0x3000, v66
	v_mul_i32_i24_e32 v84, 0x3000, v66
	v_lshl_add_u64 v[84:85], s[0:1], 0, v[84:85]
	v_lshl_add_u64 v[84:85], v[84:85], 0, v[64:65]
	s_mov_b64 s[8:9], 0x2000
	v_lshl_add_u64 v[84:85], v[84:85], 0, s[8:9]
	global_load_dwordx4 v[88:91], v[84:85], off
	v_add_u32_e32 v78, 0xffffff00, v78
	v_mov_b32_e32 v79, 0
	v_lshlrev_b64 v[78:79], 12, v[78:79]
	v_mov_b32_e32 v86, v77
	v_mov_b32_e32 v87, 0
	v_lshlrev_b64 v[86:87], 23, v[86:87]
	v_lshl_add_u64 v[86:87], v[86:87], 0, v[78:79]
	v_lshl_add_u64 v[86:87], v[86:87], 0, v[64:65]
	v_mov_b32_e32 v92, s21
	v_mov_b32_e32 v93, s20
	v_lshl_add_u64 v[92:93], v[92:93], 0, v[86:87]
	v_lshl_add_u64 v[94:95], s[36:37], 0, v[86:87]
	global_load_dwordx4 v[218:221], v[92:93], off
	s_mov_b64 s[8:9], 0x8000
	v_lshl_add_u64 v[84:85], v[92:93], 0, s[8:9]
	global_load_dwordx4 v[222:225], v[84:85], off
	s_mov_b64 s[8:9], 0x10000
	v_lshl_add_u64 v[84:85], v[92:93], 0, s[8:9]
	global_load_dwordx4 v[226:229], v[84:85], off
	s_mov_b64 s[8:9], 0x18000
	v_lshl_add_u64 v[84:85], v[92:93], 0, s[8:9]
	global_load_dwordx4 v[230:233], v[84:85], off
	s_mov_b64 s[8:9], 0x20000
	v_lshl_add_u64 v[84:85], v[92:93], 0, s[8:9]
	global_load_dwordx4 v[234:237], v[84:85], off
	s_mov_b64 s[8:9], 0x28000
	v_lshl_add_u64 v[84:85], v[92:93], 0, s[8:9]
	global_load_dwordx4 v[238:241], v[84:85], off
	s_mov_b64 s[8:9], 0x30000
	v_lshl_add_u64 v[84:85], v[92:93], 0, s[8:9]
	global_load_dwordx4 v[242:245], v[84:85], off
	s_mov_b64 s[8:9], 0x38000
	v_lshl_add_u64 v[84:85], v[92:93], 0, s[8:9]
	global_load_dwordx4 v[246:249], v[84:85], off
	ds_read_b128 v[108:111], v67
	ds_read_b128 v[112:115], v67 offset:4224
	ds_read_b128 v[116:119], v67 offset:8448
	ds_read_b128 v[120:123], v67 offset:12672
	s_waitcnt vmcnt(7) lgkmcnt(3)
	v_pk_fma_f32 v[108:109], v[108:109], v[88:89], v[218:219]
	v_pk_fma_f32 v[110:111], v[110:111], v[90:91], v[220:221]
	global_store_dwordx4 v[94:95], v[108:111], off
	s_mov_b64 s[8:9], 0x80000
	v_lshl_add_u64 v[86:87], v[92:93], 0, s[8:9]
	global_load_dwordx4 v[218:221], v[86:87], off
	ds_read_b128 v[108:111], v67 offset:16896
	s_waitcnt vmcnt(8) lgkmcnt(3)
	v_pk_fma_f32 v[112:113], v[112:113], v[88:89], v[222:223]
	v_pk_fma_f32 v[114:115], v[114:115], v[90:91], v[224:225]
	s_mov_b64 s[8:9], 0x8000
	v_lshl_add_u64 v[84:85], v[94:95], 0, s[8:9]
	global_store_dwordx4 v[84:85], v[112:115], off
	s_mov_b64 s[8:9], 0x88000
	v_lshl_add_u64 v[86:87], v[92:93], 0, s[8:9]
	global_load_dwordx4 v[222:225], v[86:87], off
	ds_read_b128 v[112:115], v67 offset:21120
	s_waitcnt vmcnt(9) lgkmcnt(3)
;   DI void operator()(int mt, int nt, int wm, int wn, int r, int h, f32x16 (&acc)[WM][2]) const {
;     ...
; #pragma unroll 4
;       for (int j = 0; j < 16; ++j) {
;         const int id = tid + 256 * j;
;         const int lr = id >> 5, cc = id & 31;
;         const int row = mt * (WM * 64) + (lr >> 6) * (WM * 32) + ps * 64 + (lr & 63);
;         const int b = row / NTOK, t = row % NTOK;
;         const bool isctx = t < NCTX;
;         if (isctx && l == 1) continue;
;         const int col = nt * 128 + cc * 4;
;         const float4 a = *(const float4*)(T + lr * LD + cc * 4);
;         const float4 g = *(const float4*)(MOD + ((size_t)l * 9 + (isctx ? 8 : b)) * 3072 + 2048 + col);
;         const float4 xo = *(const float4*)(xsrc_row(*p, l, b, t) + col);
;         float* dst = (isctx ? (float*)(p->ws + WS_XRC) + ((size_t)b * NCTX + t) * DM : p->out + ((size_t)b * NLAT + (t - NCTX)) * DM) + col;
;         *(float4*)dst = make_float4(xo.x + g.x * a.x, xo.y + g.y * a.y, xo.z + g.z * a.z, xo.w + g.w * a.w);
	v_pk_fma_f32 v[116:117], v[116:117], v[88:89], v[226:227]
	v_pk_fma_f32 v[118:119], v[118:119], v[90:91], v[228:229]
	s_mov_b64 s[8:9], 0x10000
	v_lshl_add_u64 v[84:85], v[94:95], 0, s[8:9]
	global_store_dwordx4 v[84:85], v[116:119], off
	s_mov_b64 s[8:9], 0x90000
	v_lshl_add_u64 v[86:87], v[92:93], 0, s[8:9]
	global_load_dwordx4 v[226:229], v[86:87], off
	ds_read_b128 v[116:119], v67 offset:25344
	s_waitcnt vmcnt(10) lgkmcnt(3)
	v_pk_fma_f32 v[120:121], v[120:121], v[88:89], v[230:231]
	v_pk_fma_f32 v[122:123], v[122:123], v[90:91], v[232:233]
	s_mov_b64 s[8:9], 0x18000
	v_lshl_add_u64 v[84:85], v[94:95], 0, s[8:9]
	global_store_dwordx4 v[84:85], v[120:123], off
	s_mov_b64 s[8:9], 0x98000
	v_lshl_add_u64 v[86:87], v[92:93], 0, s[8:9]
	global_load_dwordx4 v[230:233], v[86:87], off
	ds_read_b128 v[120:123], v67 offset:29568
	s_waitcnt vmcnt(11) lgkmcnt(3)
	v_pk_fma_f32 v[108:109], v[108:109], v[88:89], v[234:235]
	v_pk_fma_f32 v[110:111], v[110:111], v[90:91], v[236:237]
	s_mov_b64 s[8:9], 0x20000
	v_lshl_add_u64 v[84:85], v[94:95], 0, s[8:9]
	global_store_dwordx4 v[84:85], v[108:111], off
	s_mov_b64 s[8:9], 0xa0000
	v_lshl_add_u64 v[86:87], v[92:93], 0, s[8:9]
	global_load_dwordx4 v[234:237], v[86:87], off
	ds_read_b128 v[108:111], v67 offset:33792
	s_waitcnt vmcnt(12) lgkmcnt(3)
	v_pk_fma_f32 v[112:113], v[112:113], v[88:89], v[238:239]
	v_pk_fma_f32 v[114:115], v[114:115], v[90:91], v[240:241]
	s_mov_b64 s[8:9], 0x28000
	v_lshl_add_u64 v[84:85], v[94:95], 0, s[8:9]
	global_store_dwordx4 v[84:85], v[112:115], off
	s_mov_b64 s[8:9], 0xa8000
	v_lshl_add_u64 v[86:87], v[92:93], 0, s[8:9]
	global_load_dwordx4 v[238:241], v[86:87], off
	ds_read_b128 v[112:115], v67 offset:38016
	s_waitcnt vmcnt(13) lgkmcnt(3)
	v_pk_fma_f32 v[116:117], v[116:117], v[88:89], v[242:243]
	v_pk_fma_f32 v[118:119], v[118:119], v[90:91], v[244:245]
	s_mov_b64 s[8:9], 0x30000
	v_lshl_add_u64 v[84:85], v[94:95], 0, s[8:9]
	global_store_dwordx4 v[84:85], v[116:119], off
	s_mov_b64 s[8:9], 0xb0000
	v_lshl_add_u64 v[86:87], v[92:93], 0, s[8:9]
	global_load_dwordx4 v[242:245], v[86:87], off
	ds_read_b128 v[116:119], v67 offset:42240
	s_waitcnt vmcnt(14) lgkmcnt(3)
	v_pk_fma_f32 v[120:121], v[120:121], v[88:89], v[246:247]
	v_pk_fma_f32 v[122:123], v[122:123], v[90:91], v[248:249]
	s_mov_b64 s[8:9], 0x38000
	v_lshl_add_u64 v[84:85], v[94:95], 0, s[8:9]
	global_store_dwordx4 v[84:85], v[120:123], off
	s_mov_b64 s[8:9], 0xb8000
	v_lshl_add_u64 v[86:87], v[92:93], 0, s[8:9]
	global_load_dwordx4 v[246:249], v[86:87], off
	ds_read_b128 v[120:123], v67 offset:46464
	s_waitcnt vmcnt(14) lgkmcnt(3)
	v_pk_fma_f32 v[108:109], v[108:109], v[88:89], v[218:219]
	v_pk_fma_f32 v[110:111], v[110:111], v[90:91], v[220:221]
	s_mov_b64 s[8:9], 0x80000
	v_lshl_add_u64 v[84:85], v[94:95], 0, s[8:9]
	global_store_dwordx4 v[84:85], v[108:111], off
	s_nop 1
	ds_read_b128 v[108:111], v67 offset:50688
	s_waitcnt vmcnt(13) lgkmcnt(3)
	v_pk_fma_f32 v[112:113], v[112:113], v[88:89], v[222:223]
	v_pk_fma_f32 v[114:115], v[114:115], v[90:91], v[224:225]
	s_mov_b64 s[8:9], 0x88000
	v_lshl_add_u64 v[84:85], v[94:95], 0, s[8:9]
	global_store_dwordx4 v[84:85], v[112:115], off
	s_nop 1
	ds_read_b128 v[112:115], v67 offset:54912
	s_waitcnt vmcnt(12) lgkmcnt(3)
	v_pk_fma_f32 v[116:117], v[116:117], v[88:89], v[226:227]
	v_pk_fma_f32 v[118:119], v[118:119], v[90:91], v[228:229]
	s_mov_b64 s[8:9], 0x90000
	v_lshl_add_u64 v[84:85], v[94:95], 0, s[8:9]
	global_store_dwordx4 v[84:85], v[116:119], off
	s_nop 1
	ds_read_b128 v[116:119], v67 offset:59136
	s_waitcnt vmcnt(11) lgkmcnt(3)
	v_pk_fma_f32 v[120:121], v[120:121], v[88:89], v[230:231]
	v_pk_fma_f32 v[122:123], v[122:123], v[90:91], v[232:233]
	s_mov_b64 s[8:9], 0x98000
	v_lshl_add_u64 v[84:85], v[94:95], 0, s[8:9]
	global_store_dwordx4 v[84:85], v[120:123], off
	s_nop 1
	ds_read_b128 v[120:123], v67 offset:63360
	s_waitcnt vmcnt(10) lgkmcnt(3)
	v_pk_fma_f32 v[108:109], v[108:109], v[88:89], v[234:235]
	v_pk_fma_f32 v[110:111], v[110:111], v[90:91], v[236:237]
	s_mov_b64 s[8:9], 0xa0000
	v_lshl_add_u64 v[84:85], v[94:95], 0, s[8:9]
	global_store_dwordx4 v[84:85], v[108:111], off
	s_waitcnt vmcnt(9) lgkmcnt(2)
	v_pk_fma_f32 v[112:113], v[112:113], v[88:89], v[238:239]
	v_pk_fma_f32 v[114:115], v[114:115], v[90:91], v[240:241]
	s_mov_b64 s[8:9], 0xa8000
	v_lshl_add_u64 v[84:85], v[94:95], 0, s[8:9]
	global_store_dwordx4 v[84:85], v[112:115], off
	s_waitcnt vmcnt(8) lgkmcnt(1)
	v_pk_fma_f32 v[116:117], v[116:117], v[88:89], v[242:243]
	v_pk_fma_f32 v[118:119], v[118:119], v[90:91], v[244:245]
	s_mov_b64 s[8:9], 0xb0000
	v_lshl_add_u64 v[84:85], v[94:95], 0, s[8:9]
	global_store_dwordx4 v[84:85], v[116:119], off
	s_waitcnt vmcnt(7) lgkmcnt(0)
	v_pk_fma_f32 v[120:121], v[120:121], v[88:89], v[246:247]
	v_pk_fma_f32 v[122:123], v[122:123], v[90:91], v[248:249]
	s_mov_b64 s[8:9], 0xb8000
	v_lshl_add_u64 v[84:85], v[94:95], 0, s[8:9]
	global_store_dwordx4 v[84:85], v[120:123], off
	s_branch .LBB0_1053
